# conversion tail of the in-projection phase shortened to 6144 items on top of the nt cache-policy version
# baseline (speedup 1.0000x reference)
; __device__ __forceinline__ int conv_cnt(int t0, int t1, int t) { return (t0 <= t && t < t1) ? (t == 0 ? I_IN : t == 1 ? I_OUT : t == 2 ? I_MI : I_MO) : 0; }
; __device__ __forceinline__ void conv_stream(const ConvSrc& cs, unsigned char* ws, float sa_in, float sa_mi, float sa_out, float sb_in, int la, int a0, int a1, int lb, int b0, int b1, int it0, int it1, int gw, int NGW, int lane) {
;     const int na = conv_cnt(a0, a1, 0) + conv_cnt(a0, a1, 1) + conv_cnt(a0, a1, 2) + conv_cnt(a0, a1, 3), nb = conv_cnt(b0, b1, 0) + conv_cnt(b0, b1, 1) + conv_cnt(b0, b1, 2) + conv_cnt(b0, b1, 3), ntot = na + nb;
;     const int iend = it1 < ntot ? it1 : ntot;
;     for (int it = it0 + gw; it < iend; it += 2 * NGW) { ItemD c0, c1; f32x4 v0[16], v1[16]; const bool two = it + NGW < iend;
; __global__ void __launch_bounds__(NWAVES * 64, 2) mk_fwd(Args args) {
;     ...
;             { const int nwg = (MTOK / 256) * (DIN / 256), rem = nwg % G;
;               if (dup_ == 0 && rem > 0 && bx >= rem) { const float* qsc = (const float*)(ws + WS_WQS) + 8; const ConvSrc cs{IN_(5), IN_(6), IN_(14), IN_(15), IN_(1), IN_(3)};
;                   conv_stream(cs, ws, 0.f, qsc[3 * l + 1], qsc[3 * l + 2], (l + 1 < DEPTH) ? qsc[3 * l + 3] : 0.f, l, 1, 4, l + 1, 0, (l + 1 < DEPTH) ? 1 : 0, 0, CONV_TAIL_ITEMS, (bx - rem) * NWAVES + wave, (G - rem) * NWAVES, lane); }
.LBB0_245:
	s_waitcnt lgkmcnt(0)
	s_abs_i32 s2, s7
	v_cvt_f32_u32_e32 v0, s2
	s_sub_i32 s3, 0, s2
	v_rcp_iflag_f32_e32 v0, v0
	s_nop 0
	v_mul_f32_e32 v0, 0x4f7ffffe, v0
	v_cvt_u32_f32_e32 v0, v0
	s_nop 0
	v_readfirstlane_b32 s4, v0
	s_mul_i32 s3, s3, s4
	s_mul_hi_u32 s3, s4, s3
	s_add_i32 s4, s4, s3
	s_mul_hi_u32 s3, s4, 0x480
	s_mul_i32 s3, s3, s2
	s_sub_i32 s3, 0x480, s3
	s_sub_i32 s4, s3, s2
	s_cmp_ge_u32 s3, s2
	s_cselect_b32 s3, s4, s3
	s_sub_i32 s4, s3, s2
	s_cmp_ge_u32 s3, s2
	s_cselect_b32 s16, s4, s3
	s_cmp_eq_u32 s16, 0
	s_cselect_b64 s[2:3], -1, 0
	s_cmp_lt_i32 s88, s16
	s_cselect_b64 s[4:5], -1, 0
	s_or_b64 s[2:3], s[2:3], s[4:5]
	s_and_b64 vcc, exec, s[2:3]
	s_cbranch_vccnz .LBB0_269
	s_sub_i32 s2, s88, s16
	s_lshl_b32 s2, s2, 3
	s_add_i32 s10, s2, s1
	s_cmpk_gt_i32 s10, 0x17ff
	s_cbranch_scc1 .LBB0_269
	s_lshl_b64 s[2:3], s[12:13], 2
	s_add_u32 s2, s24, s2
	s_addc_u32 s3, s25, s3
	v_mov_b32_e32 v0, 0x120000
	global_load_dwordx2 v[128:129], v0, s[2:3] offset:36
	s_mov_b32 s4, s92
	s_mov_b32 s5, s13
	s_lshl_b64 s[2:3], s[4:5], 28
	s_lshl_b64 s[14:15], s[4:5], 26
	s_load_dwordx2 s[30:31], s[22:23], 0x8
	s_load_dwordx2 s[4:5], s[22:23], 0x18
	s_load_dwordx2 s[8:9], s[22:23], 0x70
	s_load_dwordx4 s[24:27], s[22:23], 0x28
	s_sub_i32 s17, s7, s16
	s_lshl_b32 s11, s17, 3
	s_lshl_b32 s12, s92, 12
	s_lshl_b32 s20, s17, 4
	s_waitcnt lgkmcnt(0)
	s_add_u32 s2, s8, s2
	s_addc_u32 s3, s9, s3
	s_lshl_b64 s[36:37], s[12:13], 2
	s_add_u32 s4, s4, s36
	s_addc_u32 s5, s5, s37
	s_add_u32 s8, s18, 0x6800000
	s_addc_u32 s9, s19, 0
	s_add_u32 s14, s26, s14
	s_addc_u32 s15, s27, s15
	s_add_u32 s22, s18, 0x4800000
	s_mul_i32 s38, s92, 0x9000000
	s_addc_u32 s23, s19, 0
	s_add_u32 s24, s24, s38
	s_addc_u32 s25, s25, 0
	s_add_u32 s26, s30, s36
	v_lshlrev_b32_e32 v0, 1, v166
	s_addc_u32 s27, s31, s37
	s_lshl_b32 s12, s16, 3
	s_lshl_b32 s7, s7, 3
	s_waitcnt vmcnt(0)
	v_and_b32_e32 v131, -16, v0
	v_lshlrev_b32_e32 v0, 2, v166
	s_sub_i32 s12, s1, s12
	s_add_i32 s1, s1, s7
	s_lshl_b32 s7, s16, 4
	v_and_b32_e32 v137, 28, v0
	s_sub_i32 s1, s1, s7
	v_readlane_b32 s17, v254, 43
	s_branch .LBB0_250

; __device__ __forceinline__ void conv_stream(const ConvSrc& cs, unsigned char* ws, float sa_in, float sa_mi, float sa_out, float sb_in, int la, int a0, int a1, int lb, int b0, int b1, int it0, int it1, int gw, int NGW, int lane) {
;     ...
;     for (int it = it0 + gw; it < iend; it += 2 * NGW) { ItemD c0, c1; f32x4 v0[16], v1[16]; const bool two = it + NGW < iend;
.LBB0_249:
	s_add_i32 s12, s12, s20
	v_readlane_b32 s17, v254, 43
	s_add_i32 s10, s10, s20
	s_add_i32 s16, s17, s12
	s_add_i32 s1, s1, s20
	s_cmpk_lt_i32 s16, 0x1800
	s_cbranch_scc0 .LBB0_269

; __device__ __forceinline__ int conv_cnt(int t0, int t1, int t) { return (t0 <= t && t < t1) ? (t == 0 ? I_IN : t == 1 ? I_OUT : t == 2 ? I_MI : I_MO) : 0; }
; __device__ __forceinline__ void conv_load(const ItemD& d, int lane, f32x4 (&v)[16]) {
;     const int nblk = d.N / 32, kb = d.r / nblk, nb = d.r - kb * nblk, k0 = 128 * kb + 16 * (lane >> 3), n0 = 32 * nb + 4 * (lane & 7);
; #pragma unroll
;     for (int i = 0; i < 16; ++i) v[i] = *(const f32x4*)(d.W + (size_t)(k0 + i) * d.N + n0);
; __device__ __forceinline__ void conv_decode(const ConvSrc& cs, unsigned char* ws, float sa_in, float sa_mi, float sa_out, float sb_in, int la, int a0, int a1, int lb, int b0, int b1, int na, int it, ItemD& d) {
;     const bool inA = it < na; const int l = inA ? la : lb, t0 = inA ? a0 : b0, t1 = inA ? a1 : b1; int r = inA ? it : it - na; unsigned char* wl = ws + WS_W + (size_t)l * W_LAYER_B;
;     const int n0 = conv_cnt(t0, t1, 0), n1 = conv_cnt(t0, t1, 1), n2 = conv_cnt(t0, t1, 2);
;     if (r < n0) { d = ItemD{cs.w_in + (size_t)l * DM * DIN, cs.ln_attn_pre + l * DM, wl, inA ? sa_in : sb_in, DM, DIN, r, 1}; return; } r -= n0;
; __device__ __forceinline__ void conv_stream(const ConvSrc& cs, unsigned char* ws, float sa_in, float sa_mi, float sa_out, float sb_in, int la, int a0, int a1, int lb, int b0, int b1, int it0, int it1, int gw, int NGW, int lane) {
;     ...
;     for (int it = it0 + gw; it < iend; it += 2 * NGW) { ItemD c0, c1; f32x4 v0[16], v1[16]; const bool two = it + NGW < iend;
;         conv_decode(cs, ws, sa_in, sa_mi, sa_out, sb_in, la, a0, a1, lb, b0, b1, na, it, c0); conv_load(c0, lane, v0);
;         if (two) { conv_decode(cs, ws, sa_in, sa_mi, sa_out, sb_in, la, a0, a1, lb, b0, b1, na, it + NGW, c1); conv_load(c1, lane, v1); }
.LBB0_254:
	v_readlane_b32 s16, v254, 43
	s_add_i32 s16, s16, s1
	s_cmpk_lt_i32 s16, 0x1800
	s_cselect_b64 s[40:41], -1, 0
	s_lshr_b32 s48, s17, 5
	v_cvt_f32_u32_e32 v64, s48
	s_sub_i32 s51, 0, s48
	s_abs_i32 s50, s47
	s_ashr_i32 s49, s47, 31
	v_rcp_iflag_f32_e32 v64, v64
	s_nop 0
	v_mul_f32_e32 v64, 0x4f7ffffe, v64
	v_cvt_u32_f32_e32 v64, v64
	s_nop 0
	v_readfirstlane_b32 s52, v64
	s_mul_i32 s51, s51, s52
	s_mul_hi_u32 s51, s52, s51
	s_add_i32 s52, s52, s51
	s_mul_hi_u32 s51, s50, s52
	s_mul_i32 s52, s51, s48
	s_sub_i32 s50, s50, s52
	s_add_i32 s53, s51, 1
	s_sub_i32 s52, s50, s48
	s_cmp_ge_u32 s50, s48
	s_cselect_b32 s51, s53, s51
	s_cselect_b32 s50, s52, s50
	s_add_i32 s52, s51, 1
	s_cmp_ge_u32 s50, s48
	s_cselect_b32 s50, s52, s51
	s_xor_b32 s50, s50, s49
	s_sub_i32 s49, s50, s49
	s_mul_i32 s48, s49, s48
	v_lshl_add_u32 v132, s49, 7, v131
	s_sub_i32 s47, s47, s48
	v_lshl_or_b32 v134, s47, 5, v137
	v_or_b32_e32 v66, 1, v132
	v_or_b32_e32 v72, 2, v132
	v_or_b32_e32 v74, 3, v132
	v_or_b32_e32 v80, 4, v132
	v_or_b32_e32 v82, 5, v132
	v_or_b32_e32 v88, 6, v132
	v_or_b32_e32 v90, 7, v132
	v_or_b32_e32 v96, 8, v132
	v_or_b32_e32 v98, 9, v132
	v_or_b32_e32 v104, 10, v132
	v_or_b32_e32 v106, 11, v132
	v_or_b32_e32 v112, 12, v132
	v_or_b32_e32 v114, 13, v132
	v_or_b32_e32 v122, 14, v132
	v_or_b32_e32 v124, 15, v132
	v_mad_i64_i32 v[64:65], s[48:49], v132, s17, 0
	v_ashrrev_i32_e32 v135, 31, v134
	v_mad_i64_i32 v[66:67], s[48:49], v66, s17, 0
	v_mad_i64_i32 v[72:73], s[48:49], v72, s17, 0
	v_mad_i64_i32 v[74:75], s[48:49], v74, s17, 0
	v_mad_i64_i32 v[80:81], s[48:49], v80, s17, 0
	v_mad_i64_i32 v[82:83], s[48:49], v82, s17, 0
	v_mad_i64_i32 v[88:89], s[48:49], v88, s17, 0
	v_mad_i64_i32 v[90:91], s[48:49], v90, s17, 0
	v_mad_i64_i32 v[96:97], s[48:49], v96, s17, 0
	v_mad_i64_i32 v[98:99], s[48:49], v98, s17, 0
	v_mad_i64_i32 v[104:105], s[48:49], v104, s17, 0
	v_mad_i64_i32 v[106:107], s[48:49], v106, s17, 0
	v_mad_i64_i32 v[112:113], s[48:49], v112, s17, 0
	v_mad_i64_i32 v[114:115], s[48:49], v114, s17, 0
	v_mad_i64_i32 v[122:123], s[48:49], v122, s17, 0
	v_mad_i64_i32 v[124:125], s[48:49], v124, s17, 0
	v_lshl_add_u64 v[64:65], v[64:65], 2, s[44:45]
	v_lshlrev_b64 v[120:121], 2, v[134:135]
	v_lshl_add_u64 v[66:67], v[66:67], 2, s[44:45]
	v_lshl_add_u64 v[72:73], v[72:73], 2, s[44:45]
	v_lshl_add_u64 v[74:75], v[74:75], 2, s[44:45]
	v_lshl_add_u64 v[80:81], v[80:81], 2, s[44:45]
	v_lshl_add_u64 v[82:83], v[82:83], 2, s[44:45]
	v_lshl_add_u64 v[88:89], v[88:89], 2, s[44:45]
	v_lshl_add_u64 v[90:91], v[90:91], 2, s[44:45]
	v_lshl_add_u64 v[96:97], v[96:97], 2, s[44:45]
	v_lshl_add_u64 v[98:99], v[98:99], 2, s[44:45]
	v_lshl_add_u64 v[104:105], v[104:105], 2, s[44:45]
	v_lshl_add_u64 v[106:107], v[106:107], 2, s[44:45]
	v_lshl_add_u64 v[112:113], v[112:113], 2, s[44:45]
	v_lshl_add_u64 v[114:115], v[114:115], 2, s[44:45]
	v_lshl_add_u64 v[122:123], v[122:123], 2, s[44:45]
	v_lshl_add_u64 v[124:125], v[124:125], 2, s[44:45]
	v_lshl_add_u64 v[64:65], v[64:65], 0, v[120:121]
	v_lshl_add_u64 v[66:67], v[66:67], 0, v[120:121]
	v_lshl_add_u64 v[72:73], v[72:73], 0, v[120:121]
	v_lshl_add_u64 v[74:75], v[74:75], 0, v[120:121]
	v_lshl_add_u64 v[80:81], v[80:81], 0, v[120:121]
	v_lshl_add_u64 v[82:83], v[82:83], 0, v[120:121]
	v_lshl_add_u64 v[88:89], v[88:89], 0, v[120:121]
	v_lshl_add_u64 v[90:91], v[90:91], 0, v[120:121]
	v_lshl_add_u64 v[96:97], v[96:97], 0, v[120:121]
	v_lshl_add_u64 v[98:99], v[98:99], 0, v[120:121]
	v_lshl_add_u64 v[104:105], v[104:105], 0, v[120:121]
	v_lshl_add_u64 v[106:107], v[106:107], 0, v[120:121]
	v_lshl_add_u64 v[112:113], v[112:113], 0, v[120:121]
	v_lshl_add_u64 v[114:115], v[114:115], 0, v[120:121]
	v_lshl_add_u64 v[122:123], v[122:123], 0, v[120:121]
	v_lshl_add_u64 v[120:121], v[124:125], 0, v[120:121]
	global_load_dwordx4 v[68:71], v[64:65], off nt
	s_nop 0
	global_load_dwordx4 v[64:67], v[66:67], off nt
	s_nop 0
	global_load_dwordx4 v[76:79], v[72:73], off nt
	s_nop 0
	global_load_dwordx4 v[72:75], v[74:75], off nt
	s_nop 0
	global_load_dwordx4 v[84:87], v[80:81], off nt
	s_nop 0
	global_load_dwordx4 v[80:83], v[82:83], off nt
	s_nop 0
	global_load_dwordx4 v[92:95], v[88:89], off nt
	s_nop 0
	global_load_dwordx4 v[88:91], v[90:91], off nt
	s_nop 0
	global_load_dwordx4 v[100:103], v[96:97], off nt
	s_nop 0
	global_load_dwordx4 v[96:99], v[98:99], off nt
	s_nop 0
	global_load_dwordx4 v[108:111], v[104:105], off nt
	s_nop 0
	global_load_dwordx4 v[104:107], v[106:107], off nt
	s_nop 0
	global_load_dwordx4 v[116:119], v[112:113], off nt
	s_nop 0
	global_load_dwordx4 v[112:115], v[114:115], off nt
	s_nop 0
	global_load_dwordx4 v[124:127], v[122:123], off nt
	s_nop 0
	global_load_dwordx4 v[120:123], v[120:121], off nt
	s_cmpk_gt_i32 s16, 0x17ff
	s_cbranch_scc1 .LBB0_260
	s_add_i32 s7, s10, s11
	s_cmp_lt_i32 s16, 0
	s_cbranch_scc1 .LBB0_258
	s_mov_b64 s[30:31], 0
	s_movk_i32 s46, 0x1000
	s_cmpk_lt_u32 s16, 0x1000
	s_waitcnt vmcnt(16)
	v_mov_b32_e32 v130, v129
	s_mov_b64 s[36:37], s[22:23]
	s_mov_b64 s[44:45], s[14:15]
	s_cbranch_scc1 .LBB0_259
	s_add_i32 s7, s16, 0xfffff000
	s_movk_i32 s46, 0x4000
	v_mov_b32_e32 v130, v128
	s_mov_b64 s[36:37], s[8:9]
	s_mov_b64 s[30:31], s[4:5]
	s_mov_b64 s[44:45], s[2:3]
	s_branch .LBB0_259

; __device__ __forceinline__ int lane_id() { int l; asm volatile("v_mbcnt_lo_u32_b32 %0, -1, 0\n\tv_mbcnt_hi_u32_b32 %0, -1, %0" : "=v"(l)); return l; }
; __global__ void __launch_bounds__(NWAVES * 64, 2) mk_fwd(Args args) {
;     ...
;             const int cslot = vcu % 5; int ui = 0;
;             for (int s = vcu; s < 1280; s += G, ++ui) {
;                 if (ui == cslot) {
;                     CArgs A2 = (CArgs)__builtin_amdgcn_kernarg_segment_ptr(); asm volatile("" : "+s"(A2)); unsigned char* ws2 = A2->ws;
;                     int wv2 = wave0; asm volatile("" : "+s"(wv2)); int ln2 = lane_id(); asm volatile("" : "+v"(ln2)); const int gw2 = vcu * NWAVES + wv2;
;                     const float* qsc = (const float*)(ws2 + WS_WQS) + 8;
;                     const ConvSrc cs{A2->in[5], A2->in[6], A2->in[14], A2->in[15], A2->in[1], A2->in[3]};
;                     conv_stream(cs, ws2, 0.f, qsc[3 * l + 1], qsc[3 * l + 2], (l + 1 < DEPTH) ? qsc[3 * l + 3] : 0.f, l, 1, 4, l + 1, 0, (l + 1 < DEPTH) ? 1 : 0, (((MTOK / 256) * (DIN / 256)) % G) ? CONV_TAIL_ITEMS : 0, 1 << 30, gw2, NGW, ln2); }
.LBB0_330:
	v_writelane_b32 v254, s4, 51
	s_add_i32 s1, s22, 1
	s_mov_b32 s10, 0
	v_writelane_b32 v254, s5, 52
	s_load_dwordx2 s[4:5], s[4:5], 0x88
	s_waitcnt lgkmcnt(0)
	v_writelane_b32 v254, s4, 53
	s_nop 1
	v_writelane_b32 v254, s5, 54
	s_mul_i32 s4, s22, 3
	s_mov_b32 s5, s13
	v_writelane_b32 v254, s4, 55
	s_nop 1
	v_writelane_b32 v254, s5, 56
	v_writelane_b32 v254, s1, 57
	s_xor_b32 s1, s22, 1
	v_writelane_b32 v254, s1, 58
	s_lshl_b32 s1, s2, 3
	v_writelane_b32 v254, s1, 59
	s_mul_hi_i32 s1, s26, 0x66666667
	s_lshr_b32 s2, s1, 31
	s_ashr_i32 s1, s1, 1
	s_add_i32 s1, s1, s2
	s_mul_i32 s1, s1, 5
	s_sub_i32 s1, s26, s1
	v_writelane_b32 v254, s1, 60
	s_cmpk_gt_i32 s26, 0x4ff
	s_cbranch_scc1 .LBB0_520
	v_readlane_b32 s2, v254, 53
	v_readlane_b32 s3, v254, 54
	s_add_u32 s1, s2, 0x31800000
	v_writelane_b32 v254, s1, 61
	s_addc_u32 s1, s3, 0
	v_writelane_b32 v254, s1, 62
	s_add_u32 s1, s2, 0x3a800000
	v_writelane_b32 v254, s1, 63
	s_addc_u32 s1, s3, 0
	v_readlane_b32 s4, v254, 51
	v_readlane_b32 s5, v254, 52
	s_load_dwordx2 s[8:9], s[4:5], 0x38
	v_writelane_b32 v255, s1, 0
	s_add_u32 s1, s2, 0x52800000
	v_writelane_b32 v255, s1, 1
	s_addc_u32 s1, s3, 0
	v_readlane_b32 s2, v254, 50
	v_writelane_b32 v255, s1, 2
	s_abs_i32 s1, s2
	v_cvt_f32_u32_e32 v0, s1
	s_waitcnt lgkmcnt(0)
	v_writelane_b32 v255, s8, 3
	s_lshl_b32 s3, s22, 3
	s_lshl_b32 s2, s2, 4
	v_writelane_b32 v255, s9, 4
	s_load_dwordx2 s[8:9], s[4:5], 0x50
	v_rcp_iflag_f32_e32 v0, v0
	s_load_dwordx2 s[4:5], s[4:5], 0x68
	s_waitcnt lgkmcnt(0)
	v_writelane_b32 v255, s8, 5
	s_nop 1
	v_writelane_b32 v255, s9, 6
	v_writelane_b32 v255, s4, 7
	v_mul_f32_e32 v0, 0x4f7ffffe, v0
	v_cvt_u32_f32_e32 v0, v0
	v_writelane_b32 v255, s5, 8
	v_writelane_b32 v255, s3, 9
	v_readlane_b32 s3, v254, 48
	s_lshl_b32 s3, s3, 6
	s_nop 0
	v_writelane_b32 v255, s3, 10
	v_writelane_b32 v255, s2, 11
	s_sub_i32 s2, 0, s1
	v_readfirstlane_b32 s3, v0
	s_mul_i32 s2, s2, s3
	s_mul_hi_u32 s2, s3, s2
	s_add_i32 s3, s3, s2
	s_mul_hi_u32 s2, s3, 0x480
	s_mul_i32 s2, s2, s1
	s_sub_i32 s2, 0x480, s2
	s_sub_i32 s3, s2, s1
	s_cmp_ge_u32 s2, s1
	s_cselect_b32 s2, s3, s2
	s_sub_i32 s3, s2, s1
	s_cmp_ge_u32 s2, s1
	s_cselect_b32 s1, s3, s2
	s_cmp_eq_u32 s1, 0
	s_cselect_b32 s1, 0, 0x1800
	v_readlane_b32 s2, v254, 49
	s_add_i32 s1, s2, s1
	v_writelane_b32 v255, s1, 12
	s_branch .LBB0_333

; __device__ __forceinline__ int lane_id() { int l; asm volatile("v_mbcnt_lo_u32_b32 %0, -1, 0\n\tv_mbcnt_hi_u32_b32 %0, -1, %0" : "=v"(l)); return l; }
; __device__ __forceinline__ int conv_cnt(int t0, int t1, int t) { return (t0 <= t && t < t1) ? (t == 0 ? I_IN : t == 1 ? I_OUT : t == 2 ? I_MI : I_MO) : 0; }
; __device__ __forceinline__ void conv_stream(const ConvSrc& cs, unsigned char* ws, float sa_in, float sa_mi, float sa_out, float sb_in, int la, int a0, int a1, int lb, int b0, int b1, int it0, int it1, int gw, int NGW, int lane) {
;     const int na = conv_cnt(a0, a1, 0) + conv_cnt(a0, a1, 1) + conv_cnt(a0, a1, 2) + conv_cnt(a0, a1, 3), nb = conv_cnt(b0, b1, 0) + conv_cnt(b0, b1, 1) + conv_cnt(b0, b1, 2) + conv_cnt(b0, b1, 3), ntot = na + nb;
;     const int iend = it1 < ntot ? it1 : ntot;
; __global__ void __launch_bounds__(NWAVES * 64, 2) mk_fwd(Args args) {
;     ...
;             if (ui <= cslot) {
;                 int ln3 = lane_id(); asm volatile("" : "+v"(ln3)); const float* qsc = (const float*)(ws + WS_WQS) + 8;
;                 const ConvSrc cs{IN_(5), IN_(6), IN_(14), IN_(15), IN_(1), IN_(3)};
;                 conv_stream(cs, ws, 0.f, qsc[3 * l + 1], qsc[3 * l + 2], (l + 1 < DEPTH) ? qsc[3 * l + 3] : 0.f, l, 1, 4, l + 1, 0, (l + 1 < DEPTH) ? 1 : 0, (((MTOK / 256) * (DIN / 256)) % G) ? CONV_TAIL_ITEMS : 0, 1 << 30, gw, NGW, ln3); }
.LBB0_523:
	v_readlane_b32 s1, v254, 50
	s_abs_i32 s1, s1
	v_readlane_b32 s2, v254, 48
	v_cvt_f32_u32_e32 v1, s1
	v_readlane_b32 s3, v254, 49
	s_add_i32 s2, s3, s2
	s_sub_i32 s3, 0, s1
	v_rcp_iflag_f32_e32 v1, v1
	s_nop 0
	v_mul_f32_e32 v1, 0x4f7ffffe, v1
	v_cvt_u32_f32_e32 v1, v1
	s_nop 0
	v_readfirstlane_b32 s4, v1
	s_mul_i32 s3, s3, s4
	s_mul_hi_u32 s3, s4, s3
	s_add_i32 s4, s4, s3
	s_mul_hi_u32 s3, s4, 0x480
	s_mul_i32 s3, s3, s1
	s_sub_i32 s3, 0x480, s3
	s_sub_i32 s4, s3, s1
	s_cmp_ge_u32 s3, s1
	s_cselect_b32 s3, s4, s3
	s_sub_i32 s4, s3, s1
	s_cmp_ge_u32 s3, s1
	s_cselect_b32 s1, s4, s3
	s_cmp_eq_u32 s1, 0
	s_cselect_b32 s1, 0, 0x1800
	s_add_i32 s7, s2, s1
	s_cmp_ge_i32 s7, s0
	s_cbranch_scc1 .LBB0_588
	s_load_dwordx2 s[4:5], s[10:11], 0x8
	s_load_dwordx2 s[8:9], s[10:11], 0x18
	s_load_dwordx4 s[36:39], s[10:11], 0x28
	s_load_dwordx4 s[40:43], s[10:11], 0x70
	v_readlane_b32 s2, v254, 53
	v_readlane_b32 s3, v254, 54
	s_add_u32 s50, s2, 0x800000
	v_lshlrev_b32_e32 v1, 1, v0
	v_lshlrev_b32_e32 v0, 2, v0
	v_readlane_b32 s1, v254, 50
	s_addc_u32 s51, s3, 0
	v_and_b32_e32 v137, -16, v1
	v_and_b32_e32 v154, 28, v0
	s_lshl_b32 s52, s1, 4
	s_branch .LBB0_527
